# NSA compressed pass 1: fully valid tiles take a QK block without limit compares (on top of window fast path)
# speedup vs baseline: 1.0038x; 1.0038x over previous
; #define SB0 __builtin_amdgcn_sched_barrier(0)
; __device__ __forceinline__ void qk64_lim(const bf16x8 (&kq)[8], const bf16x8 (&qf)[2], float scale, int lim2,
;                                          f32x4 (&st)[4]) {
; #pragma unroll
;   for (int kt = 0; kt < 4; ++kt) {
;     f32x4 z = {0.f, 0.f, 0.f, 0.f};
;     z = mfma16(kq[2 * kt], qf[0], z);
;     z = mfma16(kq[2 * kt + 1], qf[1], z);
; #pragma unroll
;     for (int r = 0; r < 4; ++r) st[kt][r] = ((kt * 16 + r) <= lim2) ? z[r] * scale : -INFINITY;
;   }
; }
; __device__ __forceinline__ void phase_nsa_attn(const Params& p, char* smem, volatile LAS unsigned* vb_) {
;     ...
;         for (int i = 0; i < ntile; ++i) {
;           const int n0 = i * 64;
;           const int nn = (i + 1 < ntile ? i + 1 : i) * 64;
;           f32x4 st[4];
;           qk64_lim(kA, qf, scale, nvalid - 1 - n0 - q * 4, st);
;           SB0;
;           k_load64(kA, Kb + (size_t)nn * 64, lane);
;           SB0;
.Lc1_fast:
	s_waitcnt vmcnt(7)
	v_mfma_f32_16x16x32_bf16 v[40:43], v[40:43], v[4:7], 0
	s_add_i32 s11, s20, 1
	v_mov_b32_e32 v44, v0
	v_mov_b32_e32 v0, s20
	s_waitcnt vmcnt(6)
	v_mfma_f32_16x16x32_bf16 v[36:39], v[36:39], v[8:11], v[40:43]
	v_mov_b32_e32 v45, s11
	v_cmp_lt_i32_e32 vcc, s11, v159
	v_mov_b32_e32 v3, v180
	s_waitcnt vmcnt(5)
	v_mfma_f32_16x16x32_bf16 v[32:35], v[32:35], v[4:7], 0
	v_cndmask_b32_e32 v0, v0, v45, vcc
	s_waitcnt vmcnt(4)
	v_mfma_f32_16x16x32_bf16 v[28:31], v[28:31], v[8:11], v[32:35]
	v_lshlrev_b32_e32 v0, 6, v0
	s_nop 0
	v_mul_f32_e32 v45, 0x3e38aa3b, v36
	s_waitcnt vmcnt(3)
	v_mfma_f32_16x16x32_bf16 v[24:27], v[24:27], v[4:7], 0
	v_mul_f32_e32 v46, 0x3e38aa3b, v37
	s_waitcnt vmcnt(2)
	v_mfma_f32_16x16x32_bf16 v[20:23], v[20:23], v[8:11], v[24:27]
	v_mul_f32_e32 v47, 0x3e38aa3b, v38
	s_waitcnt vmcnt(1)
	v_mfma_f32_16x16x32_bf16 v[16:19], v[16:19], v[4:7], 0
	v_mul_f32_e32 v48, 0x3e38aa3b, v39
	s_waitcnt vmcnt(0)
	v_mfma_f32_16x16x32_bf16 v[12:15], v[12:15], v[8:11], v[16:19]
	v_mul_f32_e32 v49, 0x3e38aa3b, v28
	v_mul_f32_e32 v50, 0x3e38aa3b, v29
	v_mul_f32_e32 v51, 0x3e38aa3b, v30
	v_mul_f32_e32 v52, 0x3e38aa3b, v31
	v_mul_f32_e32 v53, 0x3e38aa3b, v20
	v_mul_f32_e32 v54, 0x3e38aa3b, v21
	v_mul_f32_e32 v55, 0x3e38aa3b, v22
	v_mul_f32_e32 v56, 0x3e38aa3b, v23
	v_mul_f32_e32 v57, 0x3e38aa3b, v12
	v_mul_f32_e32 v58, 0x3e38aa3b, v13
	v_mul_f32_e32 v59, 0x3e38aa3b, v14
	v_mul_f32_e32 v60, 0x3e38aa3b, v15
	s_branch .Lc1_tail

; #define SB0 __builtin_amdgcn_sched_barrier(0)
; __device__ __forceinline__ void qk64_lim(const bf16x8 (&kq)[8], const bf16x8 (&qf)[2], float scale, int lim2,
;                                          f32x4 (&st)[4]) {
; #pragma unroll
;   for (int kt = 0; kt < 4; ++kt) {
;     f32x4 z = {0.f, 0.f, 0.f, 0.f};
;     z = mfma16(kq[2 * kt], qf[0], z);
;     z = mfma16(kq[2 * kt + 1], qf[1], z);
; #pragma unroll
;     for (int r = 0; r < 4; ++r) st[kt][r] = ((kt * 16 + r) <= lim2) ? z[r] * scale : -INFINITY;
;   }
; }
; __device__ __forceinline__ void phase_nsa_attn(const Params& p, char* smem, volatile LAS unsigned* vb_) {
;     ...
;         for (int i = 0; i < ntile; ++i) {
;           const int n0 = i * 64;
;           const int nn = (i + 1 < ntile ? i + 1 : i) * 64;
;           f32x4 st[4];
;           qk64_lim(kA, qf, scale, nvalid - 1 - n0 - q * 4, st);
;           SB0;
;           k_load64(kA, Kb + (size_t)nn * 64, lane);
;           SB0;
.LBB0_94:
	v_readfirstlane_b32 s98, v2
	s_cmp_gt_i32 s98, 62
	s_cbranch_scc1 .Lc1_fast
	s_waitcnt vmcnt(7)
	v_mfma_f32_16x16x32_bf16 v[40:43], v[40:43], v[4:7], 0
	s_add_i32 s11, s20, 1
	v_mov_b32_e32 v44, v0
	v_mov_b32_e32 v0, s20
	s_waitcnt vmcnt(6)
	v_mfma_f32_16x16x32_bf16 v[36:39], v[36:39], v[8:11], v[40:43]
	v_mov_b32_e32 v45, s11
	v_cmp_lt_i32_e32 vcc, s11, v159
	v_mov_b32_e32 v3, v180
	s_waitcnt vmcnt(5)
	v_mfma_f32_16x16x32_bf16 v[32:35], v[32:35], v[4:7], 0
	v_cndmask_b32_e32 v0, v0, v45, vcc
	s_nop 1
	v_mul_f32_e32 v36, 0x3e38aa3b, v36
	v_cmp_lt_i32_e32 vcc, -1, v2
	s_waitcnt vmcnt(4)
	v_mfma_f32_16x16x32_bf16 v[28:31], v[28:31], v[8:11], v[32:35]
	v_lshlrev_b32_e32 v0, 6, v0
	v_cndmask_b32_e32 v45, v203, v36, vcc
	v_mul_f32_e32 v36, 0x3e38aa3b, v37
	s_waitcnt vmcnt(3)
	v_mfma_f32_16x16x32_bf16 v[24:27], v[24:27], v[4:7], 0
	v_cmp_lt_i32_e32 vcc, 0, v2
	s_nop 1
	v_mul_f32_e32 v28, 0x3e38aa3b, v28
	v_cndmask_b32_e32 v46, v203, v36, vcc
	v_mul_f32_e32 v36, 0x3e38aa3b, v38
	v_cmp_lt_i32_e32 vcc, 1, v2
	s_waitcnt vmcnt(2)
	v_mfma_f32_16x16x32_bf16 v[20:23], v[20:23], v[8:11], v[24:27]
	v_cndmask_b32_e32 v47, v203, v36, vcc
	v_mul_f32_e32 v36, 0x3e38aa3b, v39
	v_cmp_lt_i32_e32 vcc, 2, v2
	s_waitcnt vmcnt(1)
	v_mfma_f32_16x16x32_bf16 v[16:19], v[16:19], v[4:7], 0
	s_nop 2
	v_mul_f32_e32 v20, 0x3e38aa3b, v20
	v_cndmask_b32_e32 v48, v203, v36, vcc
	v_cmp_lt_i32_e32 vcc, 15, v2
	s_waitcnt vmcnt(0)
	v_mfma_f32_16x16x32_bf16 v[12:15], v[12:15], v[8:11], v[16:19]
	v_cndmask_b32_e32 v49, v203, v28, vcc
	v_mul_f32_e32 v28, 0x3e38aa3b, v29
	v_cmp_lt_i32_e32 vcc, 16, v2
	s_nop 1
	v_cndmask_b32_e32 v50, v203, v28, vcc
	v_mul_f32_e32 v28, 0x3e38aa3b, v30
	v_cmp_lt_i32_e32 vcc, 17, v2
	v_mul_f32_e32 v12, 0x3e38aa3b, v12
	s_nop 0
	v_cndmask_b32_e32 v51, v203, v28, vcc
	v_mul_f32_e32 v28, 0x3e38aa3b, v31
	v_cmp_lt_i32_e32 vcc, 18, v2
	s_nop 1
	v_cndmask_b32_e32 v52, v203, v28, vcc
	v_cmp_lt_i32_e32 vcc, 31, v2
	s_nop 1
	v_cndmask_b32_e32 v53, v203, v20, vcc
	v_mul_f32_e32 v20, 0x3e38aa3b, v21
	v_cmp_lt_i32_e32 vcc, 32, v2
	s_nop 1
	v_cndmask_b32_e32 v54, v203, v20, vcc
	v_mul_f32_e32 v20, 0x3e38aa3b, v22
	v_cmp_lt_i32_e32 vcc, 33, v2
	s_nop 1
	v_cndmask_b32_e32 v55, v203, v20, vcc
	v_mul_f32_e32 v20, 0x3e38aa3b, v23
	v_cmp_lt_i32_e32 vcc, 34, v2
	s_nop 1
	v_cndmask_b32_e32 v56, v203, v20, vcc
	v_cmp_lt_i32_e32 vcc, 47, v2
	s_nop 1
	v_cndmask_b32_e32 v57, v203, v12, vcc
	v_mul_f32_e32 v12, 0x3e38aa3b, v13
	v_cmp_lt_i32_e32 vcc, 48, v2
	s_nop 1
	v_cndmask_b32_e32 v58, v203, v12, vcc
	v_mul_f32_e32 v12, 0x3e38aa3b, v14
	v_cmp_lt_i32_e32 vcc, 49, v2
	s_nop 1
	v_cndmask_b32_e32 v59, v203, v12, vcc
	v_mul_f32_e32 v12, 0x3e38aa3b, v15
	v_cmp_lt_i32_e32 vcc, 50, v2
	s_nop 1
	v_cndmask_b32_e32 v60, v203, v12, vcc
; #define EXP2F(x) __builtin_amdgcn_exp2f(x)
; #define SB0 __builtin_amdgcn_sched_barrier(0)
; __device__ __forceinline__ void phase_nsa_attn(const Params& p, char* smem, volatile LAS unsigned* vb_) {
;     ...
;           k_load64(kA, Kb + (size_t)nn * 64, lane);
;           SB0;
;           float mx = -1e30f;
; #pragma unroll
;           for (int kt = 0; kt < 4; ++kt)
; #pragma unroll
;             for (int r = 0; r < 4; ++r) mx = fmaxf(mx, st[kt][r]);
;           mx = fmaxf(mx, __shfl_xor(mx, 16));
;           mx = fmaxf(mx, __shfl_xor(mx, 32));
;           const float mnew = fmaxf(m, mx);
;           float ps = 0.f;
; #pragma unroll
;           for (int kt = 0; kt < 4; ++kt)
; #pragma unroll
;             for (int r = 0; r < 4; ++r) ps += EXP2F(st[kt][r] - mnew);
;           lsum = lsum * EXP2F(m - mnew) + ps;
;           m = mnew;
;         }
;         lsum += __shfl_xor(lsum, 16);
;         lsum += __shfl_xor(lsum, 32);
;         const float invl = (lsum > 0.f) ? 1.0f / lsum : 0.f;
;         f32x4 o[4];
; #pragma unroll
;         for (int dt = 0; dt < 4; ++dt) o[dt] = (f32x4){0.f, 0.f, 0.f, 0.f};
;         float carry = 0.f;
;       SB0;
;         k_load64(kA, Kb, lane);
;       SB0;
;         v_load64(vA, Vb, lane);
.Lc1_tail:
	v_lshlrev_b64 v[12:13], 7, v[0:1]
	v_lshl_add_u64 v[12:13], v[122:123], 0, v[12:13]
	global_load_dwordx4 v[40:43], v[12:13], off
	global_load_dwordx4 v[36:39], v[12:13], off offset:1024
	global_load_dwordx4 v[32:35], v[12:13], off offset:2048
	global_load_dwordx4 v[28:31], v[12:13], off offset:3072
	v_add_co_u32_e32 v12, vcc, s33, v12
	s_nop 1
	v_addc_co_u32_e32 v13, vcc, 0, v13, vcc
	global_load_dwordx4 v[24:27], v[12:13], off
	global_load_dwordx4 v[20:23], v[12:13], off offset:1024
	global_load_dwordx4 v[16:19], v[12:13], off offset:2048
	s_nop 0
	global_load_dwordx4 v[12:15], v[12:13], off offset:3072
	v_max3_f32 v0, v45, s3, v46
	v_max3_f32 v0, v0, v47, v48
	v_max3_f32 v0, v0, v49, v50
	v_max3_f32 v0, v0, v51, v52
	v_max3_f32 v0, v0, v53, v54
	v_max3_f32 v0, v0, v55, v56
	v_max3_f32 v0, v0, v57, v58
	v_max3_f32 v0, v0, v59, v60
	v_mov_b32_e32 v61, v0
	v_cmp_eq_u32_e32 vcc, s11, v159
	v_subrev_u32_e32 v2, 64, v2
	s_or_b64 s[12:13], vcc, s[12:13]
	s_mov_b32 s20, s11
	v_permlane16_swap_b32_e32 v61, v0
	v_max_f32_e32 v0, v0, v61
	v_mov_b32_e32 v61, v0
	s_nop 1
	v_permlane32_swap_b32_e32 v61, v0
	v_max3_f32 v180, v3, v0, v61
	v_sub_f32_e32 v0, v45, v180
	v_sub_f32_e32 v45, v46, v180
	v_exp_f32_e32 v0, v0
	v_sub_f32_e32 v46, v47, v180
	v_exp_f32_e32 v45, v45
	v_sub_f32_e32 v47, v48, v180
	v_exp_f32_e32 v46, v46
	v_sub_f32_e32 v48, v49, v180
	v_exp_f32_e32 v47, v47
	v_sub_f32_e32 v49, v50, v180
	v_exp_f32_e32 v48, v48
	v_add_f32_e32 v0, 0, v0
	v_sub_f32_e32 v50, v51, v180
	v_exp_f32_e32 v49, v49
	v_add_f32_e32 v0, v45, v0
	v_add_f32_e32 v0, v46, v0
	v_exp_f32_e32 v45, v50
	v_sub_f32_e32 v46, v52, v180
	v_add_f32_e32 v0, v47, v0
	v_exp_f32_e32 v46, v46
	v_sub_f32_e32 v47, v53, v180
	v_add_f32_e32 v0, v48, v0
	v_exp_f32_e32 v47, v47
	v_add_f32_e32 v0, v49, v0
	v_add_f32_e32 v0, v45, v0
	v_sub_f32_e32 v45, v54, v180
	v_add_f32_e32 v0, v46, v0
	v_exp_f32_e32 v45, v45
	v_sub_f32_e32 v46, v55, v180
	v_add_f32_e32 v0, v47, v0
	v_exp_f32_e32 v46, v46
	v_sub_f32_e32 v47, v56, v180
	v_exp_f32_e32 v47, v47
	v_sub_f32_e32 v48, v57, v180
	v_exp_f32_e32 v48, v48
	v_add_f32_e32 v0, v45, v0
	v_sub_f32_e32 v45, v58, v180
	v_add_f32_e32 v0, v46, v0
	v_exp_f32_e32 v45, v45
	v_sub_f32_e32 v46, v59, v180
	v_add_f32_e32 v0, v47, v0
	v_exp_f32_e32 v46, v46
	v_sub_f32_e32 v47, v60, v180
	v_exp_f32_e32 v47, v47
	v_sub_f32_e32 v3, v3, v180
	v_add_f32_e32 v0, v48, v0
	v_exp_f32_e32 v3, v3
	v_add_f32_e32 v0, v45, v0
	v_add_f32_e32 v0, v46, v0
	v_add_f32_e32 v0, v47, v0
	v_fmac_f32_e32 v0, v44, v3
	s_andn2_b64 exec, exec, s[12:13]
	s_cbranch_execnz .LBB0_94
	s_or_b64 exec, exec, s[12:13]
	ds_bpermute_b32 v2, v167, v0
	v_mov_b32_e32 v181, 0
	s_waitcnt lgkmcnt(0)
	v_add_f32_e32 v0, v0, v2
	ds_bpermute_b32 v2, v168, v0
	s_waitcnt lgkmcnt(0)
	v_add_f32_e32 v0, v0, v2
	v_div_scale_f32 v2, s[12:13], v0, v0, 1.0
	v_rcp_f32_e32 v3, v2
	s_waitcnt vmcnt(0)
	v_fma_f32 v12, -v2, v3, 1.0
	v_fmac_f32_e32 v3, v12, v3
	v_div_scale_f32 v12, vcc, 1.0, v0, 1.0
	v_mul_f32_e32 v13, v12, v3
	v_fma_f32 v14, -v2, v13, v12
	v_fmac_f32_e32 v13, v14, v3
	v_fma_f32 v2, -v2, v13, v12
	v_div_fmas_f32 v2, v2, v3, v13
	v_div_fixup_f32 v2, v2, v0, 1.0
	v_cmp_lt_f32_e32 vcc, 0, v0
	s_nop 1
	v_cndmask_b32_e32 v2, 0, v2, vcc
	global_load_dwordx4 v[68:71], v[122:123], off
	global_load_dwordx4 v[64:67], v[122:123], off offset:1024
	global_load_dwordx4 v[60:63], v[122:123], off offset:2048
	global_load_dwordx4 v[52:55], v[122:123], off offset:3072
	global_load_dwordx4 v[44:47], v[124:125], off
	global_load_dwordx4 v[40:43], v[126:127], off
	global_load_dwordx4 v[36:39], v[128:129], off
	global_load_dwordx4 v[32:35], v[130:131], off
	global_load_dwordx4 v[24:27], v[132:133], off
	global_load_dwordx4 v[12:15], v[132:133], off offset:1024
	global_load_dwordx4 v[80:83], v[132:133], off offset:2048
	global_load_dwordx4 v[84:87], v[132:133], off offset:3072
	global_load_dwordx4 v[28:31], v[134:135], off
	global_load_dwordx4 v[20:23], v[136:137], off
	global_load_dwordx4 v[88:91], v[138:139], off
	global_load_dwordx4 v[16:19], v[140:141], off
	v_mov_b32_e32 v3, v2
	s_mov_b32 s11, 0
	s_mov_b64 s[12:13], 0
	v_mov_b32_e32 v182, v176
	v_mov_b32_e32 v76, 0
	v_mov_b32_e32 v77, v181
	v_mov_b32_e32 v78, v181
	v_mov_b32_e32 v79, v181
	v_mov_b32_e32 v48, 0
	v_mov_b32_e32 v49, v181
	v_mov_b32_e32 v50, v181
	v_mov_b32_e32 v51, v181
	v_mov_b32_e32 v56, 0
	v_mov_b32_e32 v57, v181
	v_mov_b32_e32 v58, v181
	v_mov_b32_e32 v59, v181
	v_mov_b32_e32 v72, 0
	v_mov_b32_e32 v73, v181
	v_mov_b32_e32 v74, v181
	v_mov_b32_e32 v75, v181
	s_branch .LBB0_97
